# scaled-state scan + DCE + producer idles 768 cycles after its LDS writes
# speedup vs baseline: 1.0119x; 1.0063x over previous
; __device__ __forceinline__ float scan_prepare(const ScanRegs& R, const u32x2 qr_, const u32x2 qk_, const u32x2 qv_, LAS float* slot, int cq, const f32x4 mur, const f32x4 muk, const f32x4 muv, const f32x4 kkc, const f32x4 kac, const f32x4 rkc) {
;     float pr[4], pk[4], pv[4], qr[4], qk[4], qv[4], av[4], om[4];
;     unpack4(R.pr, pr); unpack4(R.pk, pk); unpack4(R.pv, pv); unpack4(qr_, qr); unpack4(qk_, qk); unpack4(qv_, qv); unpack4(R.as, av);
;     om[0] = f16_to_f((unsigned short)(R.wl.x & 0xffffu)); om[1] = f16_to_f((unsigned short)(R.wl.x >> 16)); om[2] = f16_to_f((unsigned short)(R.wl.y & 0xffffu)); om[3] = f16_to_f((unsigned short)(R.wl.y >> 16));
;     float rr[4], vv[4], kn[4], k2[4], dec[4], bu[4];
;     float ssq = 0.f, bon = 0.f, c1 = 0.f, c2 = 0.f;
; #pragma unroll
;     for (int j = 0; j < 4; ++j) {
;         rr[j] = pr[j] + (qr[j] - pr[j]) * mur[j]; const float kk0 = pk[j] + (qk[j] - pk[j]) * muk[j]; vv[j] = pv[j] + (qv[j] - pv[j]) * muv[j];
;         dec[j] = 1.0f - om[j];
;         kn[j] = kk0 * kkc[j]; ssq += kn[j] * kn[j];
;         k2[j] = kk0 * (1.0f + (av[j] - 1.0f) * kac[j]);
;         const float t = rr[j] * k2[j]; bon += t * rkc[j]; c2 += t;
;         bu[j] = kn[j] * av[j]; c1 += bu[j] * rr[j];
;     }
;     ssq += dpp_f<0x121>(ssq); bon += dpp_f<0x121>(bon); c1 += dpp_f<0x121>(c1); c2 += dpp_f<0x121>(c2);
;     ssq += dpp_f<0x122>(ssq); bon += dpp_f<0x122>(bon); c1 += dpp_f<0x122>(c1); c2 += dpp_f<0x122>(c2);
; __device__ __forceinline__ void p8_scan(const Args& a, LAS unsigned char* lds) {
;     ...
;             ScanRegs A0, A1, B0, B1;
;             { const size_t tok = (size_t)b * T + 2 * ltt; scan_issue(A0, PRKV, WLOG, ASIG, tok, ch, ltt > 0 ? 1 : 2); scan_issue(A1, PRKV, WLOG, ASIG, tok + 1, ch, 0);
;               const float b0 = scan_prepare(A0, A0.qr, A0.qk, A0.qv, buf + (2 * ltt) * SPITCH, cq, mur, muk, muv, kkc, kac, rkc);
;               const float b1 = scan_prepare(A1, A0.pr, A0.pk, A0.pv, buf + (2 * ltt + 1) * SPITCH, cq, mur, muk, muv, kkc, kac, rkc);
;               if (rq == 0 && cq == 0) { BONUS[tok * 16 + h] = b0; BONUS[(tok + 1) * 16 + h] = b1; }
;               scan_issue(A0, PRKV, WLOG, ASIG, tok + TC, ch, 1); scan_issue(A1, PRKV, WLOG, ASIG, tok + TC + 1, ch, 0);
;               scan_issue(B0, PRKV, WLOG, ASIG, tok + 2 * TC, ch, 1); scan_issue(B1, PRKV, WLOG, ASIG, tok + 2 * TC + 1, ch, 0); }
.LBB0_1097:
	s_or_b64 exec, exec, s[44:45]
	v_lshlrev_b32_e32 v32, 11, v139
	v_mov_b32_e32 v33, v29
	v_lshl_add_u64 v[42:43], s[90:91], 0, v[32:33]
	v_lshl_add_u64 v[42:43], v[42:43], 0, v[28:29]
	global_load_dwordx2 v[60:61], v[42:43], off
	v_lshl_add_u64 v[36:37], s[8:9], 0, v[32:33]
	v_lshl_add_u64 v[36:37], v[36:37], 0, v[28:29]
	s_mov_b64 s[44:45], 0x1800
	global_load_dwordx2 v[62:63], v[36:37], off
	v_or_b32_e32 v1, 1, v139
	s_waitcnt vmcnt(3)
	v_lshlrev_b32_e32 v46, 16, v38
	v_and_b32_e32 v47, 0xffff0000, v38
	s_waitcnt vmcnt(2)
	v_lshlrev_b32_e32 v36, 16, v52
	v_and_b32_e32 v37, 0xffff0000, v52
	v_lshlrev_b32_e32 v44, 16, v39
	v_and_b32_e32 v45, 0xffff0000, v39
	v_lshlrev_b32_e32 v38, 16, v53
	v_and_b32_e32 v39, 0xffff0000, v53
	v_lshlrev_b32_e32 v52, 16, v55
	v_and_b32_e32 v53, 0xffff0000, v55
	v_lshl_add_u64 v[34:35], v[34:35], 0, s[44:45]
	v_mov_b32_e32 v57, v29
	v_lshlrev_b32_e32 v58, 16, v54
	v_and_b32_e32 v59, 0xffff0000, v54
	v_lshlrev_b32_e32 v54, 16, v50
	v_and_b32_e32 v55, 0xffff0000, v50
	v_lshlrev_b32_e32 v50, 16, v51
	v_and_b32_e32 v51, 0xffff0000, v51
	s_movk_i32 s43, 0x1000
	v_lshlrev_b32_e32 v56, 11, v1
	v_pk_add_f32 v[52:53], v[52:53], v[38:39] neg_lo:[0,1] neg_hi:[0,1]
	v_lshl_add_u64 v[72:73], v[34:35], 0, v[28:29]
	v_lshlrev_b32_e32 v42, 16, v40
	v_and_b32_e32 v43, 0xffff0000, v40
	v_lshlrev_b32_e32 v64, 16, v48
	v_and_b32_e32 v65, 0xffff0000, v48
	v_pk_add_f32 v[70:71], v[50:51], v[44:45] neg_lo:[0,1] neg_hi:[0,1]
	v_lshl_add_u64 v[50:51], s[8:9], 0, v[56:57]
	v_lshl_add_u64 v[56:57], s[90:91], 0, v[56:57]
	v_pk_fma_f32 v[66:67], v[8:9], v[52:53], v[38:39]
	v_add_co_u32_e32 v52, vcc, s43, v72
	v_pk_add_f32 v[58:59], v[58:59], v[36:37] neg_lo:[0,1] neg_hi:[0,1]
	v_pk_add_f32 v[54:55], v[54:55], v[46:47] neg_lo:[0,1] neg_hi:[0,1]
	v_pk_add_f32 v[68:69], v[64:65], v[42:43] neg_lo:[0,1] neg_hi:[0,1]
	v_addc_co_u32_e32 v53, vcc, 0, v73, vcc
	v_lshl_add_u64 v[56:57], v[56:57], 0, v[28:29]
	v_pk_fma_f32 v[64:65], v[6:7], v[58:59], v[36:37]
	v_pk_fma_f32 v[74:75], v[2:3], v[54:55], v[46:47]
	v_pk_fma_f32 v[84:85], v[10:11], v[68:69], v[42:43]
	v_lshl_add_u64 v[68:69], v[50:51], 0, v[28:29]
	global_load_dwordx2 v[50:51], v[72:73], off
	global_load_dwordx2 v[54:55], v[72:73], off offset:2048
	global_load_dwordx2 v[58:59], v[52:53], off
	s_nop 0
	global_load_dwordx2 v[52:53], v[68:69], off
	s_nop 0
	global_load_dwordx2 v[56:57], v[56:57], off
	v_pk_fma_f32 v[70:71], v[4:5], v[70:71], v[44:45]
	v_pk_mul_f32 v[76:77], v[14:15], v[74:75]
	v_pk_mul_f32 v[78:79], v[16:17], v[70:71]
	v_pk_mul_f32 v[68:69], v[76:77], v[76:77]
	v_pk_mul_f32 v[72:73], v[78:79], v[78:79]
	v_add_f32_e32 v33, v68, v69
	v_add_f32_e32 v33, v72, v33
	v_add_f32_e32 v33, v73, v33
	v_lshlrev_b32_e32 v40, 16, v41
	v_and_b32_e32 v41, 0xffff0000, v41
	v_add_f32_dpp v33, v33, v33 row_ror:1 row_mask:0xf bank_mask:0xf bound_ctrl:1
	s_waitcnt vmcnt(6)
	v_lshlrev_b32_e32 v68, 16, v60
	v_and_b32_e32 v69, 0xffff0000, v60
	v_pk_add_f32 v[80:81], v[68:69], -1.0 op_sel_hi:[1,0]
	v_add_f32_dpp v33, v33, v33 row_ror:2 row_mask:0xf bank_mask:0xf bound_ctrl:1
	v_pk_mul_f32 v[86:87], v[76:77], v[68:69]
	v_pk_fma_f32 v[68:69], v[18:19], v[80:81], 1.0 op_sel_hi:[1,1,0]
	v_add_f32_dpp v33, v33, v33 row_ror:4 row_mask:0xf bank_mask:0xf bound_ctrl:1
	v_pk_mul_f32 v[68:69], v[74:75], v[68:69]
	s_nop 0
	v_add_f32_dpp v33, v33, v33 row_ror:8 row_mask:0xf bank_mask:0xf bound_ctrl:1
	v_pk_mul_f32 v[74:75], v[84:85], v[68:69]
	v_max_f32_e32 v33, 0x179abe15, v33
	v_lshlrev_b32_e32 v60, 16, v61
	v_and_b32_e32 v61, 0xffff0000, v61
	v_pk_add_f32 v[82:83], v[60:61], -1.0 op_sel_hi:[1,0]
	v_fma_f32 v91, v22, v74, 0
	v_rsq_f32_e32 v48, v33
	v_fmac_f32_e32 v91, v23, v75
	v_pk_fma_f32 v[74:75], v[20:21], v[82:83], 1.0 op_sel_hi:[1,1,0]
	v_pk_mul_f32 v[60:61], v[78:79], v[60:61]
	v_pk_mul_f32 v[70:71], v[70:71], v[74:75]
	v_lshlrev_b32_e32 v74, 16, v49
	v_and_b32_e32 v75, 0xffff0000, v49
	v_pk_add_f32 v[74:75], v[74:75], v[40:41] neg_lo:[0,1] neg_hi:[0,1]
	v_pk_mul_f32 v[80:81], v[86:87], v[48:49] op_sel_hi:[1,0]
	v_pk_fma_f32 v[86:87], v[12:13], v[74:75], v[40:41]
	s_waitcnt vmcnt(5)
	v_cvt_f32_f16_e32 v72, v62
	v_cvt_f32_f16_sdwa v73, v62 dst_sel:DWORD dst_unused:UNUSED_PAD src0_sel:WORD_1
	v_pk_mul_f32 v[82:83], v[60:61], v[48:49] op_sel_hi:[1,0]
	v_cvt_f32_f16_e32 v62, v63
	v_cvt_f32_f16_sdwa v63, v63 dst_sel:DWORD dst_unused:UNUSED_PAD src0_sel:WORD_1
	v_pk_mul_f32 v[88:89], v[86:87], v[70:71]
	v_pk_mul_f32 v[78:79], v[78:79], v[48:49] op_sel_hi:[1,0] neg_lo:[0,1] neg_hi:[0,1]
	v_pk_mul_f32 v[76:77], v[76:77], v[48:49] op_sel_hi:[1,0] neg_lo:[0,1] neg_hi:[0,1]
	v_fmac_f32_e32 v91, v24, v88
	v_fmac_f32_e32 v91, v25, v89
	s_nop 0
	s_nop 0
	v_add_f32_dpp v60, v91, v91 row_ror:1 row_mask:0xf bank_mask:0xf bound_ctrl:1
	v_pk_add_f32 v[74:75], v[62:63], 1.0 op_sel_hi:[1,0] neg_lo:[1,0] neg_hi:[1,0]
	s_nop 0
	v_add_f32_dpp v60, v60, v60 row_ror:2 row_mask:0xf bank_mask:0xf bound_ctrl:1
	s_nop 1
	v_add_f32_dpp v33, v60, v60 row_ror:4 row_mask:0xf bank_mask:0xf bound_ctrl:1
	v_mov_b32_e32 v49, v29
	v_pk_add_f32 v[72:73], v[72:73], 1.0 op_sel_hi:[1,0] neg_lo:[1,0] neg_hi:[1,0]
	s_nop 0
	v_mov_b32_dpp v49, v33 row_ror:8 row_mask:0xf bank_mask:0xf
	v_pk_mul_f32 v[84:85], v[84:85], 1.0 op_sel_hi:[1,0]
	v_pk_mul_f32 v[86:87], v[86:87], 1.0 op_sel_hi:[1,0]
	v_pk_mov_b32 v[174:175], v[72:73], v[72:73] op_sel:[0,1]
	v_pk_mov_b32 v[176:177], v[74:75], v[74:75] op_sel:[0,1]
	v_pk_mov_b32 v[178:179], v[68:69], v[68:69] op_sel:[0,1]
	v_pk_mov_b32 v[180:181], v[70:71], v[70:71] op_sel:[0,1]
	v_pk_mov_b32 v[182:183], v[76:77], v[76:77] op_sel:[0,1]
	v_pk_mov_b32 v[184:185], v[78:79], v[78:79] op_sel:[0,1]
	v_pk_mov_b32 v[186:187], v[80:81], v[80:81] op_sel:[0,1]
	v_pk_mov_b32 v[188:189], v[82:83], v[82:83] op_sel:[0,1]
	v_pk_mov_b32 v[190:191], v[84:85], v[84:85] op_sel:[0,1]
	v_pk_mov_b32 v[192:193], v[86:87], v[86:87] op_sel:[0,1]
	v_mov_b32_e32 v194, v127
	ds_write_b128 v127, v[64:67] offset:1280
	s_and_saveexec_b64 s[44:45], s[4:5]
	s_or_b64 exec, exec, s[44:45]
	s_waitcnt vmcnt(2)
; #define LAS __attribute__((address_space(3)))
; __device__ __forceinline__ float scan_prepare(const ScanRegs& R, const u32x2 qr_, const u32x2 qk_, const u32x2 qv_, LAS float* slot, int cq, const f32x4 mur, const f32x4 muk, const f32x4 muv, const f32x4 kkc, const f32x4 kac, const f32x4 rkc) {
;     float pr[4], pk[4], pv[4], qr[4], qk[4], qv[4], av[4], om[4];
;     unpack4(R.pr, pr); unpack4(R.pk, pk); unpack4(R.pv, pv); unpack4(qr_, qr); unpack4(qk_, qk); unpack4(qv_, qv); unpack4(R.as, av);
;     om[0] = f16_to_f((unsigned short)(R.wl.x & 0xffffu)); om[1] = f16_to_f((unsigned short)(R.wl.x >> 16)); om[2] = f16_to_f((unsigned short)(R.wl.y & 0xffffu)); om[3] = f16_to_f((unsigned short)(R.wl.y >> 16));
;     float rr[4], vv[4], kn[4], k2[4], dec[4], bu[4];
;     float ssq = 0.f, bon = 0.f, c1 = 0.f, c2 = 0.f;
; #pragma unroll
;     for (int j = 0; j < 4; ++j) {
;         rr[j] = pr[j] + (qr[j] - pr[j]) * mur[j]; const float kk0 = pk[j] + (qk[j] - pk[j]) * muk[j]; vv[j] = pv[j] + (qv[j] - pv[j]) * muv[j];
;         dec[j] = 1.0f - om[j];
;         kn[j] = kk0 * kkc[j]; ssq += kn[j] * kn[j];
;         k2[j] = kk0 * (1.0f + (av[j] - 1.0f) * kac[j]);
;         const float t = rr[j] * k2[j]; bon += t * rkc[j]; c2 += t;
;         bu[j] = kn[j] * av[j]; c1 += bu[j] * rr[j];
;     }
;     ssq += dpp_f<0x121>(ssq); bon += dpp_f<0x121>(bon); c1 += dpp_f<0x121>(c1); c2 += dpp_f<0x121>(c2);
;     ssq += dpp_f<0x122>(ssq); bon += dpp_f<0x122>(bon); c1 += dpp_f<0x122>(c1); c2 += dpp_f<0x122>(c2);
;     ssq += dpp_f<0x124>(ssq); bon += dpp_f<0x124>(bon); c1 += dpp_f<0x124>(c1); c2 += dpp_f<0x124>(c2);
;     ssq += dpp_f<0x128>(ssq); bon += dpp_f<0x128>(bon); c1 += dpp_f<0x128>(c1); c2 += dpp_f<0x128>(c2);
;     const float inv = __builtin_amdgcn_rsqf(fmaxf(ssq, 1e-24f));
;     f32x4 o_al, o_be, o_wr;
; #pragma unroll
;     for (int j = 0; j < 4; ++j) { o_al[j] = -(kn[j] * inv); o_be[j] = bu[j] * inv; o_wr[j] = dec[j] * rr[j]; }
;     LAS f32x4* s4 = (LAS f32x4*)slot;
;     s4[cq] = (f32x4){dec[0], dec[1], dec[2], dec[3]}; s4[16 + cq] = (f32x4){k2[0], k2[1], k2[2], k2[3]}; s4[32 + cq] = o_al; s4[48 + cq] = o_be; s4[64 + cq] = o_wr;
;     s4[80 + cq] = (f32x4){vv[0], vv[1], vv[2], vv[3]};
;     if (cq == 0) *(LAS f32x2*)(slot + 384) = (f32x2){c1 * inv, c2};
;     return bon;
; }
	v_lshlrev_b32_e32 v70, 16, v58
	v_and_b32_e32 v71, 0xffff0000, v58
	v_lshlrev_b32_e32 v72, 16, v59
	v_and_b32_e32 v73, 0xffff0000, v59
	v_lshlrev_b32_e32 v58, 16, v54
	v_and_b32_e32 v59, 0xffff0000, v54
	v_pk_add_f32 v[46:47], v[46:47], v[58:59] neg_lo:[0,1] neg_hi:[0,1]
	s_waitcnt vmcnt(0)
	v_lshlrev_b32_e32 v60, 16, v56
	v_pk_fma_f32 v[46:47], v[2:3], v[46:47], v[58:59]
	v_and_b32_e32 v61, 0xffff0000, v56
	v_pk_mul_f32 v[64:65], v[14:15], v[46:47]
	v_pk_add_f32 v[58:59], v[60:61], -1.0 op_sel_hi:[1,0]
	v_pk_mul_f32 v[74:75], v[64:65], v[60:61]
	v_lshlrev_b32_e32 v60, 16, v50
	v_and_b32_e32 v61, 0xffff0000, v50
	v_pk_fma_f32 v[58:59], v[18:19], v[58:59], 1.0 op_sel_hi:[1,1,0]
	v_pk_add_f32 v[42:43], v[42:43], v[60:61] neg_lo:[0,1] neg_hi:[0,1]
	v_pk_mul_f32 v[58:59], v[46:47], v[58:59]
	v_pk_fma_f32 v[76:77], v[10:11], v[42:43], v[60:61]
	v_pk_mul_f32 v[66:67], v[64:65], v[64:65]
	v_pk_mul_f32 v[42:43], v[76:77], v[58:59]
	v_cvt_f32_f16_sdwa v47, v52 dst_sel:DWORD dst_unused:UNUSED_PAD src0_sel:WORD_1
	v_fma_f32 v48, v22, v42, 0
	v_fmac_f32_e32 v48, v23, v43
	v_lshlrev_b32_e32 v42, 16, v55
	v_and_b32_e32 v43, 0xffff0000, v55
	v_pk_add_f32 v[44:45], v[44:45], v[42:43] neg_lo:[0,1] neg_hi:[0,1]
	v_cvt_f32_f16_e32 v46, v52
	v_pk_fma_f32 v[44:45], v[4:5], v[44:45], v[42:43]
	v_add_f32_e32 v50, v66, v67
	v_pk_mul_f32 v[54:55], v[16:17], v[44:45]
	v_pk_add_f32 v[62:63], v[46:47], 1.0 op_sel_hi:[1,0] neg_lo:[1,0] neg_hi:[1,0]
	v_pk_mul_f32 v[42:43], v[54:55], v[54:55]
	v_add_f32_e32 v42, v42, v50
	v_add_f32_e32 v42, v43, v42
	s_nop 0
	s_nop 0
	v_add_f32_dpp v42, v42, v42 row_ror:1 row_mask:0xf bank_mask:0xf bound_ctrl:1
	v_lshlrev_b32_e32 v46, 16, v57
	v_and_b32_e32 v47, 0xffff0000, v57
	v_add_f32_dpp v42, v42, v42 row_ror:2 row_mask:0xf bank_mask:0xf bound_ctrl:1
	v_pk_add_f32 v[56:57], v[46:47], -1.0 op_sel_hi:[1,0]
	v_cvt_f32_f16_e32 v50, v53
	v_add_f32_dpp v42, v42, v42 row_ror:4 row_mask:0xf bank_mask:0xf bound_ctrl:1
	v_pk_fma_f32 v[56:57], v[20:21], v[56:57], 1.0 op_sel_hi:[1,1,0]
	v_pk_add_f32 v[36:37], v[36:37], v[70:71] neg_lo:[0,1] neg_hi:[0,1]
	v_add_f32_dpp v42, v42, v42 row_ror:8 row_mask:0xf bank_mask:0xf bound_ctrl:1
	v_max_f32_e32 v42, 0x179abe15, v42
	v_rsq_f32_e32 v42, v42
	v_pk_mul_f32 v[60:61], v[44:45], v[56:57]
	v_pk_mul_f32 v[44:45], v[54:55], v[46:47]
	v_lshlrev_b32_e32 v46, 16, v51
	v_and_b32_e32 v47, 0xffff0000, v51
	v_pk_add_f32 v[40:41], v[40:41], v[46:47] neg_lo:[0,1] neg_hi:[0,1]
	v_cvt_f32_f16_sdwa v51, v53 dst_sel:DWORD dst_unused:UNUSED_PAD src0_sel:WORD_1
	v_pk_fma_f32 v[52:53], v[12:13], v[40:41], v[46:47]
	v_pk_mul_f32 v[68:69], v[44:45], v[42:43] op_sel_hi:[1,0]
	v_pk_mul_f32 v[40:41], v[52:53], v[60:61]
	v_pk_mul_f32 v[56:57], v[54:55], v[42:43] op_sel_hi:[1,0] neg_lo:[0,1] neg_hi:[0,1]
	v_pk_mul_f32 v[54:55], v[64:65], v[42:43] op_sel_hi:[1,0] neg_lo:[0,1] neg_hi:[0,1]
	v_pk_mul_f32 v[66:67], v[74:75], v[42:43] op_sel_hi:[1,0]
	v_fmac_f32_e32 v48, v24, v40
	v_fmac_f32_e32 v48, v25, v41
	s_nop 0
	s_nop 0
	v_add_f32_dpp v43, v48, v48 row_ror:1 row_mask:0xf bank_mask:0xf bound_ctrl:1
	s_nop 1
	v_add_f32_dpp v43, v43, v43 row_ror:2 row_mask:0xf bank_mask:0xf bound_ctrl:1
	s_nop 1
	v_add_f32_dpp v40, v43, v43 row_ror:4 row_mask:0xf bank_mask:0xf bound_ctrl:1
	v_mov_b32_e32 v41, v29
	v_pk_add_f32 v[38:39], v[38:39], v[72:73] neg_lo:[0,1] neg_hi:[0,1]
	v_pk_add_f32 v[64:65], v[50:51], 1.0 op_sel_hi:[1,0] neg_lo:[1,0] neg_hi:[1,0]
	v_mov_b32_dpp v41, v40 row_ror:8 row_mask:0xf bank_mask:0xf
	v_pk_fma_f32 v[38:39], v[8:9], v[38:39], v[72:73]
	v_pk_fma_f32 v[36:37], v[6:7], v[36:37], v[70:71]
	v_pk_mul_f32 v[50:51], v[76:77], 1.0 op_sel_hi:[1,0]
	v_pk_mul_f32 v[52:53], v[52:53], 1.0 op_sel_hi:[1,0]
	ds_write_b128 v129, v[36:39] offset:1280
	v_pk_mul_f32 v[196:197], v[174:175], v[62:63]
	v_pk_mul_f32 v[198:199], v[176:177], v[64:65]
	ds_bpermute_b32 v200, v233, v196
	ds_bpermute_b32 v201, v233, v197
	ds_bpermute_b32 v202, v233, v198
	ds_bpermute_b32 v203, v233, v199
	s_waitcnt lgkmcnt(0)
	v_fma_f32 v200, v200, v235, v236
	v_fma_f32 v201, v201, v235, v236
	v_fma_f32 v202, v202, v235, v236
	v_fma_f32 v203, v203, v235, v236
	v_pk_mul_f32 v[204:205], v[196:197], v[200:201]
	v_pk_mul_f32 v[206:207], v[198:199], v[202:203]
	v_mov_b32_e32 v208, v204
	v_mov_b32_e32 v209, v205
	v_mov_b32_e32 v210, v206
	v_mov_b32_e32 v211, v207
	v_permlane32_swap_b32 v204, v208
	v_permlane32_swap_b32 v205, v209
	v_permlane32_swap_b32 v206, v210
	v_permlane32_swap_b32 v207, v211
	v_fma_f32 v208, v204, v237, v238
	v_fma_f32 v209, v205, v237, v238
	v_fma_f32 v210, v206, v237, v238
	v_fma_f32 v211, v207, v237, v238
	v_pk_mul_f32 v[212:213], v[200:201], v[208:209]
	v_pk_mul_f32 v[214:215], v[202:203], v[210:211]
	v_pk_mul_f32 v[216:217], v[212:213], v[174:175]
	v_pk_mul_f32 v[218:219], v[214:215], v[176:177]
	v_pk_mul_f32 v[220:221], v[216:217], v[62:63]
	v_pk_mul_f32 v[222:223], v[218:219], v[64:65]
	v_rcp_f32_e32 v224, v216
	v_rcp_f32_e32 v225, v217
	v_rcp_f32_e32 v226, v218
	v_rcp_f32_e32 v227, v219
	v_rcp_f32_e32 v228, v220
	v_rcp_f32_e32 v229, v221
	v_rcp_f32_e32 v230, v222
	v_rcp_f32_e32 v231, v223
	s_nop 0
	v_pk_mul_f32 v[182:183], v[182:183], v[212:213]
	v_pk_mul_f32 v[184:185], v[184:185], v[214:215]
	v_pk_mul_f32 v[178:179], v[178:179], v[224:225]
	v_pk_mul_f32 v[180:181], v[180:181], v[226:227]
	ds_write_b128 v194, v[178:181] offset:256
	v_pk_mul_f32 v[186:187], v[186:187], v[224:225]
	v_pk_mul_f32 v[188:189], v[188:189], v[226:227]
	ds_write_b128 v194, v[182:185] offset:512
	v_pk_mul_f32 v[190:191], v[190:191], v[216:217]
	v_pk_mul_f32 v[192:193], v[192:193], v[218:219]
	ds_write_b128 v194, v[186:189] offset:768
	v_pk_mul_f32 v[240:241], v[58:59], v[228:229]
	v_pk_mul_f32 v[242:243], v[60:61], v[230:231]
	ds_write_b128 v194, v[190:193] offset:1024
	v_pk_mul_f32 v[244:245], v[54:55], v[216:217]
	v_pk_mul_f32 v[246:247], v[56:57], v[218:219]
	ds_write_b128 v129, v[220:223]
	v_pk_mul_f32 v[196:197], v[66:67], v[228:229]
	v_pk_mul_f32 v[198:199], v[68:69], v[230:231]
	ds_write_b128 v129, v[240:243] offset:256
	v_pk_mul_f32 v[200:201], v[50:51], v[220:221]
	v_pk_mul_f32 v[202:203], v[52:53], v[222:223]
	ds_write_b128 v129, v[244:247] offset:512
	ds_write_b128 v129, v[196:199] offset:768
	ds_write_b128 v129, v[200:203] offset:1024
	s_sleep 12
	s_and_saveexec_b64 s[44:45], s[4:5]
	s_mov_b64 s[84:85], s[56:57]
	s_or_b64 exec, exec, s[44:45]
	s_cmp_lt_u32 s71, 64
	s_cselect_b64 s[44:45], -1, 0
	s_and_b64 s[44:45], s[4:5], s[44:45]
	s_xor_b64 s[52:53], s[44:45], -1
	v_mov_b64_e32 v[100:101], s[14:15]
	s_and_saveexec_b64 s[56:57], s[52:53]
	s_xor_b64 s[52:53], exec, s[56:57]
	v_mov_b64_e32 v[100:101], s[14:15]
	s_andn2_saveexec_b64 s[52:53], s[52:53]
	s_cbranch_execz .LBB0_1105
; __device__ __forceinline__ void p8_scan(const Args& a, LAS unsigned char* lds) {
;     ...
;               if (rq == 0 && cq == 0) { BONUS[tok * 16 + h] = b0; BONUS[(tok + 1) * 16 + h] = b1; }
	v_lshlrev_b32_e32 v38, 6, v139
	v_mov_b32_e32 v39, v29
	v_lshlrev_b32_e32 v36, 6, v1
	v_mov_b32_e32 v37, v29
	s_lshl_b32 s14, s14, 2
	v_lshl_add_u64 v[38:39], s[12:13], 0, v[38:39]
	v_add_f32_e32 v33, v33, v49
	v_lshl_add_u64 v[36:37], s[12:13], 0, v[36:37]
	v_lshl_add_u64 v[38:39], v[38:39], 0, s[14:15]
	v_lshl_add_u64 v[36:37], v[36:37], 0, s[14:15]
	v_add_f32_e32 v1, v40, v41
	global_store_dword v[38:39], v33, off
	global_store_dword v[36:37], v1, off

; #define LAS __attribute__((address_space(3)))
; __device__ __forceinline__ float scan_prepare(const ScanRegs& R, const u32x2 qr_, const u32x2 qk_, const u32x2 qv_, LAS float* slot, int cq, const f32x4 mur, const f32x4 muk, const f32x4 muv, const f32x4 kkc, const f32x4 kac, const f32x4 rkc) {
;     float pr[4], pk[4], pv[4], qr[4], qk[4], qv[4], av[4], om[4];
;     unpack4(R.pr, pr); unpack4(R.pk, pk); unpack4(R.pv, pv); unpack4(qr_, qr); unpack4(qk_, qk); unpack4(qv_, qv); unpack4(R.as, av);
;     om[0] = f16_to_f((unsigned short)(R.wl.x & 0xffffu)); om[1] = f16_to_f((unsigned short)(R.wl.x >> 16)); om[2] = f16_to_f((unsigned short)(R.wl.y & 0xffffu)); om[3] = f16_to_f((unsigned short)(R.wl.y >> 16));
;     float rr[4], vv[4], kn[4], k2[4], dec[4], bu[4];
;     float ssq = 0.f, bon = 0.f, c1 = 0.f, c2 = 0.f;
; #pragma unroll
;     for (int j = 0; j < 4; ++j) {
;         rr[j] = pr[j] + (qr[j] - pr[j]) * mur[j]; const float kk0 = pk[j] + (qk[j] - pk[j]) * muk[j]; vv[j] = pv[j] + (qv[j] - pv[j]) * muv[j];
;         dec[j] = 1.0f - om[j];
;         kn[j] = kk0 * kkc[j]; ssq += kn[j] * kn[j];
;         k2[j] = kk0 * (1.0f + (av[j] - 1.0f) * kac[j]);
;         const float t = rr[j] * k2[j]; bon += t * rkc[j]; c2 += t;
;         bu[j] = kn[j] * av[j]; c1 += bu[j] * rr[j];
;     }
;     ssq += dpp_f<0x121>(ssq); bon += dpp_f<0x121>(bon); c1 += dpp_f<0x121>(c1); c2 += dpp_f<0x121>(c2);
;     ssq += dpp_f<0x122>(ssq); bon += dpp_f<0x122>(bon); c1 += dpp_f<0x122>(c1); c2 += dpp_f<0x122>(c2);
;     ssq += dpp_f<0x124>(ssq); bon += dpp_f<0x124>(bon); c1 += dpp_f<0x124>(c1); c2 += dpp_f<0x124>(c2);
;     ssq += dpp_f<0x128>(ssq); bon += dpp_f<0x128>(bon); c1 += dpp_f<0x128>(c1); c2 += dpp_f<0x128>(c2);
;     const float inv = __builtin_amdgcn_rsqf(fmaxf(ssq, 1e-24f));
;     f32x4 o_al, o_be, o_wr;
; #pragma unroll
;     for (int j = 0; j < 4; ++j) { o_al[j] = -(kn[j] * inv); o_be[j] = bu[j] * inv; o_wr[j] = dec[j] * rr[j]; }
;     LAS f32x4* s4 = (LAS f32x4*)slot;
;     s4[cq] = (f32x4){dec[0], dec[1], dec[2], dec[3]}; s4[16 + cq] = (f32x4){k2[0], k2[1], k2[2], k2[3]}; s4[32 + cq] = o_al; s4[48 + cq] = o_be; s4[64 + cq] = o_wr;
;     s4[80 + cq] = (f32x4){vv[0], vv[1], vv[2], vv[3]};
;     if (cq == 0) *(LAS f32x2*)(slot + 384) = (f32x2){c1 * inv, c2};
;     return bon;
; }
.LBB0_1109:
	s_waitcnt vmcnt(8)
	v_lshlrev_b32_e32 v108, 16, v46
	v_and_b32_e32 v109, 0xffff0000, v46
	v_lshlrev_b32_e32 v110, 16, v38
	v_and_b32_e32 v111, 0xffff0000, v38
	v_pk_add_f32 v[110:111], v[110:111], v[108:109] neg_lo:[0,1] neg_hi:[0,1]
	v_lshlrev_b32_e32 v140, 16, v39
	v_pk_fma_f32 v[144:145], v[6:7], v[110:111], v[108:109]
	v_lshlrev_b32_e32 v110, 16, v47
	v_and_b32_e32 v111, 0xffff0000, v47
	v_and_b32_e32 v141, 0xffff0000, v39
	v_pk_add_f32 v[140:141], v[140:141], v[110:111] neg_lo:[0,1] neg_hi:[0,1]
	v_lshlrev_b32_e32 v118, 16, v40
	v_and_b32_e32 v119, 0xffff0000, v40
	v_pk_fma_f32 v[146:147], v[8:9], v[140:141], v[110:111]
	v_lshlrev_b32_e32 v140, 16, v34
	v_and_b32_e32 v141, 0xffff0000, v34
	s_waitcnt vmcnt(3)
	v_lshlrev_b32_e32 v142, 16, v48
	v_and_b32_e32 v143, 0xffff0000, v48
	v_pk_add_f32 v[140:141], v[140:141], v[118:119] neg_lo:[0,1] neg_hi:[0,1]
	v_pk_add_f32 v[148:149], v[142:143], -1.0 op_sel_hi:[1,0]
	v_pk_fma_f32 v[140:141], v[2:3], v[140:141], v[118:119]
	v_pk_fma_f32 v[148:149], v[18:19], v[148:149], 1.0 op_sel_hi:[1,1,0]
	v_pk_mul_f32 v[154:155], v[14:15], v[140:141]
	v_pk_mul_f32 v[148:149], v[148:149], v[140:141]
	v_cvt_f32_f16_sdwa v141, v44 dst_sel:DWORD dst_unused:UNUSED_PAD src0_sel:WORD_1
	v_cvt_f32_f16_e32 v140, v44
	v_lshlrev_b32_e32 v114, 16, v36
	v_and_b32_e32 v115, 0xffff0000, v36
	v_lshlrev_b32_e32 v156, 16, v42
	v_and_b32_e32 v157, 0xffff0000, v42
	v_pk_add_f32 v[152:153], v[140:141], 1.0 op_sel_hi:[1,0] neg_lo:[1,0] neg_hi:[1,0]
	v_pk_add_f32 v[140:141], v[156:157], v[114:115] neg_lo:[0,1] neg_hi:[0,1]
	v_lshlrev_b32_e32 v116, 16, v41
	v_pk_fma_f32 v[164:165], v[10:11], v[140:141], v[114:115]
	v_and_b32_e32 v117, 0xffff0000, v41
	v_pk_mul_f32 v[140:141], v[164:165], v[148:149]
	v_pk_mul_f32 v[150:151], v[154:155], v[154:155]
	v_fma_f32 v33, v22, v140, 0
	v_fmac_f32_e32 v33, v23, v141
	v_lshlrev_b32_e32 v140, 16, v35
	v_and_b32_e32 v141, 0xffff0000, v35
	v_pk_add_f32 v[140:141], v[140:141], v[116:117] neg_lo:[0,1] neg_hi:[0,1]
	v_add_f32_e32 v28, v150, v151
	v_pk_fma_f32 v[140:141], v[4:5], v[140:141], v[116:117]
	v_pk_mul_f32 v[142:143], v[154:155], v[142:143]
	v_pk_mul_f32 v[158:159], v[16:17], v[140:141]
	v_pk_mul_f32 v[160:161], v[158:159], v[158:159]
	v_add_f32_e32 v28, v160, v28
	v_add_f32_e32 v28, v161, v28
	v_lshlrev_b32_e32 v156, 16, v49
	s_nop 0
	v_add_f32_dpp v28, v28, v28 row_ror:1 row_mask:0xf bank_mask:0xf bound_ctrl:1
	v_and_b32_e32 v157, 0xffff0000, v49
	v_lshlrev_b32_e32 v112, 16, v37
	v_add_f32_dpp v28, v28, v28 row_ror:2 row_mask:0xf bank_mask:0xf bound_ctrl:1
	v_and_b32_e32 v113, 0xffff0000, v37
	v_pk_add_f32 v[162:163], v[156:157], -1.0 op_sel_hi:[1,0]
	v_add_f32_dpp v28, v28, v28 row_ror:4 row_mask:0xf bank_mask:0xf bound_ctrl:1
	v_pk_fma_f32 v[150:151], v[20:21], v[162:163], 1.0 op_sel_hi:[1,1,0]
	v_pk_mul_f32 v[164:165], v[164:165], 1.0 op_sel_hi:[1,0]
	v_add_f32_dpp v28, v28, v28 row_ror:8 row_mask:0xf bank_mask:0xf bound_ctrl:1
	v_max_f32_e32 v28, 0x179abe15, v28
	v_rsq_f32_e32 v28, v28
	v_pk_mul_f32 v[150:151], v[150:151], v[140:141]
	v_pk_mul_f32 v[140:141], v[158:159], v[156:157]
	v_pk_mul_f32 v[160:161], v[142:143], v[28:29] op_sel_hi:[1,0]
	v_lshlrev_b32_e32 v142, 16, v43
	v_and_b32_e32 v143, 0xffff0000, v43
	v_pk_add_f32 v[142:143], v[142:143], v[112:113] neg_lo:[0,1] neg_hi:[0,1]
	v_pk_mul_f32 v[162:163], v[140:141], v[28:29] op_sel_hi:[1,0]
	v_pk_fma_f32 v[166:167], v[12:13], v[142:143], v[112:113]
	v_pk_mul_f32 v[156:157], v[154:155], v[28:29] op_sel_hi:[1,0] neg_lo:[0,1] neg_hi:[0,1]
	v_pk_mul_f32 v[142:143], v[166:167], v[150:151]
	v_fmac_f32_e32 v33, v24, v142
	v_cvt_f32_f16_sdwa v155, v45 dst_sel:DWORD dst_unused:UNUSED_PAD src0_sel:WORD_1
	v_cvt_f32_f16_e32 v154, v45
	v_fmac_f32_e32 v33, v25, v143
	s_nop 1
	v_add_f32_dpp v33, v33, v33 row_ror:1 row_mask:0xf bank_mask:0xf bound_ctrl:1
	s_nop 1
	v_add_f32_dpp v33, v33, v33 row_ror:2 row_mask:0xf bank_mask:0xf bound_ctrl:1
	s_nop 1
	v_add_f32_dpp v33, v33, v33 row_ror:4 row_mask:0xf bank_mask:0xf bound_ctrl:1
	v_mov_b32_e32 v81, 0
	v_pk_add_f32 v[154:155], v[154:155], 1.0 op_sel_hi:[1,0] neg_lo:[1,0] neg_hi:[1,0]
	s_nop 0
	v_mov_b32_dpp v81, v33 row_ror:8 row_mask:0xf bank_mask:0xf
	v_pk_mul_f32 v[158:159], v[158:159], v[28:29] op_sel_hi:[1,0] neg_lo:[0,1] neg_hi:[0,1]
	v_pk_mul_f32 v[166:167], v[166:167], 1.0 op_sel_hi:[1,0]
	v_pk_mov_b32 v[174:175], v[152:153], v[152:153] op_sel:[0,1]
	v_pk_mov_b32 v[176:177], v[154:155], v[154:155] op_sel:[0,1]
	v_pk_mov_b32 v[178:179], v[148:149], v[148:149] op_sel:[0,1]
	v_pk_mov_b32 v[180:181], v[150:151], v[150:151] op_sel:[0,1]
	v_pk_mov_b32 v[182:183], v[156:157], v[156:157] op_sel:[0,1]
	v_pk_mov_b32 v[184:185], v[158:159], v[158:159] op_sel:[0,1]
	v_pk_mov_b32 v[186:187], v[160:161], v[160:161] op_sel:[0,1]
	v_pk_mov_b32 v[188:189], v[162:163], v[162:163] op_sel:[0,1]
	v_pk_mov_b32 v[190:191], v[164:165], v[164:165] op_sel:[0,1]
	v_pk_mov_b32 v[192:193], v[166:167], v[166:167] op_sel:[0,1]
	v_mov_b32_e32 v194, v127
	ds_write_b128 v127, v[144:147] offset:51456
	s_and_saveexec_b64 s[52:53], s[4:5]
	s_or_b64 exec, exec, s[52:53]
	s_waitcnt vmcnt(17)
	v_lshlrev_b32_e32 v140, 16, v50
	v_and_b32_e32 v141, 0xffff0000, v50
	s_waitcnt vmcnt(2)
	v_lshlrev_b32_e32 v142, 16, v58
	v_and_b32_e32 v143, 0xffff0000, v58
	v_pk_add_f32 v[118:119], v[118:119], v[140:141] neg_lo:[0,1] neg_hi:[0,1]
	v_lshlrev_b32_e32 v150, 16, v59
	v_pk_fma_f32 v[118:119], v[2:3], v[118:119], v[140:141]
	v_pk_add_f32 v[140:141], v[142:143], -1.0 op_sel_hi:[1,0]
	v_pk_mul_f32 v[146:147], v[14:15], v[118:119]
	v_pk_fma_f32 v[140:141], v[18:19], v[140:141], 1.0 op_sel_hi:[1,1,0]
	v_pk_mul_f32 v[152:153], v[146:147], v[142:143]
	v_pk_mul_f32 v[140:141], v[140:141], v[118:119]
	v_cvt_f32_f16_sdwa v119, v52 dst_sel:DWORD dst_unused:UNUSED_PAD src0_sel:WORD_1
	v_cvt_f32_f16_e32 v118, v52
	s_waitcnt vmcnt(6)
; #define LAS __attribute__((address_space(3)))
; __device__ __forceinline__ float scan_prepare(const ScanRegs& R, const u32x2 qr_, const u32x2 qk_, const u32x2 qv_, LAS float* slot, int cq, const f32x4 mur, const f32x4 muk, const f32x4 muv, const f32x4 kkc, const f32x4 kac, const f32x4 rkc) {
;     float pr[4], pk[4], pv[4], qr[4], qk[4], qv[4], av[4], om[4];
;     unpack4(R.pr, pr); unpack4(R.pk, pk); unpack4(R.pv, pv); unpack4(qr_, qr); unpack4(qk_, qk); unpack4(qv_, qv); unpack4(R.as, av);
;     om[0] = f16_to_f((unsigned short)(R.wl.x & 0xffffu)); om[1] = f16_to_f((unsigned short)(R.wl.x >> 16)); om[2] = f16_to_f((unsigned short)(R.wl.y & 0xffffu)); om[3] = f16_to_f((unsigned short)(R.wl.y >> 16));
;     float rr[4], vv[4], kn[4], k2[4], dec[4], bu[4];
;     float ssq = 0.f, bon = 0.f, c1 = 0.f, c2 = 0.f;
; #pragma unroll
;     for (int j = 0; j < 4; ++j) {
;         rr[j] = pr[j] + (qr[j] - pr[j]) * mur[j]; const float kk0 = pk[j] + (qk[j] - pk[j]) * muk[j]; vv[j] = pv[j] + (qv[j] - pv[j]) * muv[j];
;         dec[j] = 1.0f - om[j];
;         kn[j] = kk0 * kkc[j]; ssq += kn[j] * kn[j];
;         k2[j] = kk0 * (1.0f + (av[j] - 1.0f) * kac[j]);
;         const float t = rr[j] * k2[j]; bon += t * rkc[j]; c2 += t;
;         bu[j] = kn[j] * av[j]; c1 += bu[j] * rr[j];
;     }
;     ssq += dpp_f<0x121>(ssq); bon += dpp_f<0x121>(bon); c1 += dpp_f<0x121>(c1); c2 += dpp_f<0x121>(c2);
;     ssq += dpp_f<0x122>(ssq); bon += dpp_f<0x122>(bon); c1 += dpp_f<0x122>(c1); c2 += dpp_f<0x122>(c2);
;     ssq += dpp_f<0x124>(ssq); bon += dpp_f<0x124>(bon); c1 += dpp_f<0x124>(c1); c2 += dpp_f<0x124>(c2);
;     ssq += dpp_f<0x128>(ssq); bon += dpp_f<0x128>(bon); c1 += dpp_f<0x128>(c1); c2 += dpp_f<0x128>(c2);
;     const float inv = __builtin_amdgcn_rsqf(fmaxf(ssq, 1e-24f));
;     f32x4 o_al, o_be, o_wr;
; #pragma unroll
;     for (int j = 0; j < 4; ++j) { o_al[j] = -(kn[j] * inv); o_be[j] = bu[j] * inv; o_wr[j] = dec[j] * rr[j]; }
;     LAS f32x4* s4 = (LAS f32x4*)slot;
;     s4[cq] = (f32x4){dec[0], dec[1], dec[2], dec[3]}; s4[16 + cq] = (f32x4){k2[0], k2[1], k2[2], k2[3]}; s4[32 + cq] = o_al; s4[48 + cq] = o_be; s4[64 + cq] = o_wr;
;     s4[80 + cq] = (f32x4){vv[0], vv[1], vv[2], vv[3]};
;     if (cq == 0) *(LAS f32x2*)(slot + 384) = (f32x2){c1 * inv, c2};
;     return bon;
; }
	v_lshlrev_b32_e32 v142, 16, v82
	v_and_b32_e32 v143, 0xffff0000, v82
	v_pk_add_f32 v[114:115], v[114:115], v[142:143] neg_lo:[0,1] neg_hi:[0,1]
	v_pk_add_f32 v[144:145], v[118:119], 1.0 op_sel_hi:[1,0] neg_lo:[1,0] neg_hi:[1,0]
	v_pk_fma_f32 v[118:119], v[10:11], v[114:115], v[142:143]
	v_pk_mul_f32 v[148:149], v[146:147], v[146:147]
	v_pk_mul_f32 v[114:115], v[118:119], v[140:141]
	v_fma_f32 v156, v22, v114, 0
	v_fmac_f32_e32 v156, v23, v115
	v_lshlrev_b32_e32 v114, 16, v51
	v_and_b32_e32 v115, 0xffff0000, v51
	v_pk_add_f32 v[116:117], v[116:117], v[114:115] neg_lo:[0,1] neg_hi:[0,1]
	v_add_f32_e32 v28, v148, v149
	v_pk_fma_f32 v[114:115], v[4:5], v[116:117], v[114:115]
	v_and_b32_e32 v151, 0xffff0000, v59
	v_pk_mul_f32 v[116:117], v[16:17], v[114:115]
	v_pk_add_f32 v[154:155], v[150:151], -1.0 op_sel_hi:[1,0]
	v_pk_mul_f32 v[142:143], v[116:117], v[116:117]
	s_waitcnt vmcnt(5)
	v_lshlrev_b32_e32 v160, 16, v88
	v_add_f32_e32 v28, v142, v28
	v_add_f32_e32 v28, v143, v28
	v_pk_fma_f32 v[142:143], v[20:21], v[154:155], 1.0 op_sel_hi:[1,1,0]
	v_and_b32_e32 v161, 0xffff0000, v88
	v_add_f32_dpp v28, v28, v28 row_ror:1 row_mask:0xf bank_mask:0xf bound_ctrl:1
	v_pk_mul_f32 v[142:143], v[142:143], v[114:115]
	v_pk_mul_f32 v[114:115], v[116:117], v[150:151]
	v_add_f32_dpp v28, v28, v28 row_ror:2 row_mask:0xf bank_mask:0xf bound_ctrl:1
	v_lshlrev_b32_e32 v162, 16, v89
	v_and_b32_e32 v163, 0xffff0000, v89
	v_add_f32_dpp v28, v28, v28 row_ror:4 row_mask:0xf bank_mask:0xf bound_ctrl:1
	v_pk_add_f32 v[108:109], v[108:109], v[160:161] neg_lo:[0,1] neg_hi:[0,1]
	v_pk_add_f32 v[110:111], v[110:111], v[162:163] neg_lo:[0,1] neg_hi:[0,1]
	v_add_f32_dpp v28, v28, v28 row_ror:8 row_mask:0xf bank_mask:0xf bound_ctrl:1
	v_max_f32_e32 v28, 0x179abe15, v28
	v_rsq_f32_e32 v28, v28
	v_pk_fma_f32 v[110:111], v[8:9], v[110:111], v[162:163]
	v_pk_fma_f32 v[108:109], v[6:7], v[108:109], v[160:161]
	v_pk_mul_f32 v[150:151], v[116:117], v[28:29] op_sel_hi:[1,0] neg_lo:[0,1] neg_hi:[0,1]
	v_lshlrev_b32_e32 v116, 16, v83
	v_and_b32_e32 v117, 0xffff0000, v83
	v_pk_add_f32 v[112:113], v[112:113], v[116:117] neg_lo:[0,1] neg_hi:[0,1]
	v_pk_mul_f32 v[154:155], v[114:115], v[28:29] op_sel_hi:[1,0]
	v_pk_fma_f32 v[158:159], v[12:13], v[112:113], v[116:117]
	v_pk_mul_f32 v[148:149], v[146:147], v[28:29] op_sel_hi:[1,0] neg_lo:[0,1] neg_hi:[0,1]
	v_pk_mul_f32 v[112:113], v[158:159], v[142:143]
	v_fmac_f32_e32 v156, v24, v112
	v_cvt_f32_f16_sdwa v147, v53 dst_sel:DWORD dst_unused:UNUSED_PAD src0_sel:WORD_1
	v_cvt_f32_f16_e32 v146, v53
	v_fmac_f32_e32 v156, v25, v113
	s_nop 1
	v_add_f32_dpp v114, v156, v156 row_ror:1 row_mask:0xf bank_mask:0xf bound_ctrl:1
	s_nop 1
	v_add_f32_dpp v114, v114, v114 row_ror:2 row_mask:0xf bank_mask:0xf bound_ctrl:1
	s_nop 1
	v_add_f32_dpp v112, v114, v114 row_ror:4 row_mask:0xf bank_mask:0xf bound_ctrl:1
	v_mov_b32_e32 v113, 0
	v_pk_add_f32 v[146:147], v[146:147], 1.0 op_sel_hi:[1,0] neg_lo:[1,0] neg_hi:[1,0]
	s_nop 0
	v_mov_b32_dpp v113, v112 row_ror:8 row_mask:0xf bank_mask:0xf
	v_pk_mul_f32 v[152:153], v[152:153], v[28:29] op_sel_hi:[1,0]
	v_pk_mul_f32 v[156:157], v[118:119], 1.0 op_sel_hi:[1,0]
	v_pk_mul_f32 v[158:159], v[158:159], 1.0 op_sel_hi:[1,0]
	ds_write_b128 v129, v[108:111] offset:51456
	v_pk_mul_f32 v[196:197], v[174:175], v[144:145]
	v_pk_mul_f32 v[198:199], v[176:177], v[146:147]
	ds_bpermute_b32 v200, v233, v196
	ds_bpermute_b32 v201, v233, v197
	ds_bpermute_b32 v202, v233, v198
	ds_bpermute_b32 v203, v233, v199
	s_waitcnt lgkmcnt(0)
	v_fma_f32 v200, v200, v235, v236
	v_fma_f32 v201, v201, v235, v236
	v_fma_f32 v202, v202, v235, v236
	v_fma_f32 v203, v203, v235, v236
	v_pk_mul_f32 v[204:205], v[196:197], v[200:201]
	v_pk_mul_f32 v[206:207], v[198:199], v[202:203]
	v_mov_b32_e32 v208, v204
	v_mov_b32_e32 v209, v205
	v_mov_b32_e32 v210, v206
	v_mov_b32_e32 v211, v207
	v_permlane32_swap_b32 v204, v208
	v_permlane32_swap_b32 v205, v209
	v_permlane32_swap_b32 v206, v210
	v_permlane32_swap_b32 v207, v211
	v_fma_f32 v208, v204, v237, v238
	v_fma_f32 v209, v205, v237, v238
	v_fma_f32 v210, v206, v237, v238
	v_fma_f32 v211, v207, v237, v238
	v_pk_mul_f32 v[212:213], v[200:201], v[208:209]
	v_pk_mul_f32 v[214:215], v[202:203], v[210:211]
	v_pk_mul_f32 v[216:217], v[212:213], v[174:175]
	v_pk_mul_f32 v[218:219], v[214:215], v[176:177]
	v_pk_mul_f32 v[220:221], v[216:217], v[144:145]
	v_pk_mul_f32 v[222:223], v[218:219], v[146:147]
	v_rcp_f32_e32 v224, v216
	v_rcp_f32_e32 v225, v217
	v_rcp_f32_e32 v226, v218
	v_rcp_f32_e32 v227, v219
	v_rcp_f32_e32 v228, v220
	v_rcp_f32_e32 v229, v221
	v_rcp_f32_e32 v230, v222
	v_rcp_f32_e32 v231, v223
	s_nop 0
	v_pk_mul_f32 v[182:183], v[182:183], v[212:213]
	v_pk_mul_f32 v[184:185], v[184:185], v[214:215]
	v_pk_mul_f32 v[178:179], v[178:179], v[224:225]
	v_pk_mul_f32 v[180:181], v[180:181], v[226:227]
	ds_write_b128 v194, v[178:181] offset:50432
	v_pk_mul_f32 v[186:187], v[186:187], v[224:225]
	v_pk_mul_f32 v[188:189], v[188:189], v[226:227]
	ds_write_b128 v194, v[182:185] offset:50688
	v_pk_mul_f32 v[190:191], v[190:191], v[216:217]
	v_pk_mul_f32 v[192:193], v[192:193], v[218:219]
	ds_write_b128 v194, v[186:189] offset:50944
	v_pk_mul_f32 v[240:241], v[140:141], v[228:229]
	v_pk_mul_f32 v[242:243], v[142:143], v[230:231]
	ds_write_b128 v194, v[190:193] offset:51200
	v_pk_mul_f32 v[244:245], v[148:149], v[216:217]
	v_pk_mul_f32 v[246:247], v[150:151], v[218:219]
	ds_write_b128 v129, v[220:223] offset:50176
	v_pk_mul_f32 v[196:197], v[152:153], v[228:229]
	v_pk_mul_f32 v[198:199], v[154:155], v[230:231]
	ds_write_b128 v129, v[240:243] offset:50432
	v_pk_mul_f32 v[200:201], v[156:157], v[220:221]
	v_pk_mul_f32 v[202:203], v[158:159], v[222:223]
	ds_write_b128 v129, v[244:247] offset:50688
	ds_write_b128 v129, v[196:199] offset:50944
	ds_write_b128 v129, v[200:203] offset:51200
	s_sleep 12
	s_and_saveexec_b64 s[52:53], s[4:5]
	s_cbranch_execz .LBB0_1121
	s_or_b64 exec, exec, s[52:53]
	s_and_saveexec_b64 s[52:53], s[44:45]
	s_cbranch_execnz .LBB0_1122

; #define LAS __attribute__((address_space(3)))
; __device__ __forceinline__ float scan_prepare(const ScanRegs& R, const u32x2 qr_, const u32x2 qk_, const u32x2 qv_, LAS float* slot, int cq, const f32x4 mur, const f32x4 muk, const f32x4 muv, const f32x4 kkc, const f32x4 kac, const f32x4 rkc) {
;     float pr[4], pk[4], pv[4], qr[4], qk[4], qv[4], av[4], om[4];
;     unpack4(R.pr, pr); unpack4(R.pk, pk); unpack4(R.pv, pv); unpack4(qr_, qr); unpack4(qk_, qk); unpack4(qv_, qv); unpack4(R.as, av);
;     om[0] = f16_to_f((unsigned short)(R.wl.x & 0xffffu)); om[1] = f16_to_f((unsigned short)(R.wl.x >> 16)); om[2] = f16_to_f((unsigned short)(R.wl.y & 0xffffu)); om[3] = f16_to_f((unsigned short)(R.wl.y >> 16));
;     float rr[4], vv[4], kn[4], k2[4], dec[4], bu[4];
;     float ssq = 0.f, bon = 0.f, c1 = 0.f, c2 = 0.f;
; #pragma unroll
;     for (int j = 0; j < 4; ++j) {
;         rr[j] = pr[j] + (qr[j] - pr[j]) * mur[j]; const float kk0 = pk[j] + (qk[j] - pk[j]) * muk[j]; vv[j] = pv[j] + (qv[j] - pv[j]) * muv[j];
;         dec[j] = 1.0f - om[j];
;         kn[j] = kk0 * kkc[j]; ssq += kn[j] * kn[j];
;         k2[j] = kk0 * (1.0f + (av[j] - 1.0f) * kac[j]);
;         const float t = rr[j] * k2[j]; bon += t * rkc[j]; c2 += t;
;         bu[j] = kn[j] * av[j]; c1 += bu[j] * rr[j];
;     }
;     ssq += dpp_f<0x121>(ssq); bon += dpp_f<0x121>(bon); c1 += dpp_f<0x121>(c1); c2 += dpp_f<0x121>(c2);
;     ssq += dpp_f<0x122>(ssq); bon += dpp_f<0x122>(bon); c1 += dpp_f<0x122>(c1); c2 += dpp_f<0x122>(c2);
;     ssq += dpp_f<0x124>(ssq); bon += dpp_f<0x124>(bon); c1 += dpp_f<0x124>(c1); c2 += dpp_f<0x124>(c2);
;     ssq += dpp_f<0x128>(ssq); bon += dpp_f<0x128>(bon); c1 += dpp_f<0x128>(c1); c2 += dpp_f<0x128>(c2);
;     const float inv = __builtin_amdgcn_rsqf(fmaxf(ssq, 1e-24f));
;     f32x4 o_al, o_be, o_wr;
; #pragma unroll
;     for (int j = 0; j < 4; ++j) { o_al[j] = -(kn[j] * inv); o_be[j] = bu[j] * inv; o_wr[j] = dec[j] * rr[j]; }
;     LAS f32x4* s4 = (LAS f32x4*)slot;
;     s4[cq] = (f32x4){dec[0], dec[1], dec[2], dec[3]}; s4[16 + cq] = (f32x4){k2[0], k2[1], k2[2], k2[3]}; s4[32 + cq] = o_al; s4[48 + cq] = o_be; s4[64 + cq] = o_wr;
;     s4[80 + cq] = (f32x4){vv[0], vv[1], vv[2], vv[3]};
;     if (cq == 0) *(LAS f32x2*)(slot + 384) = (f32x2){c1 * inv, c2};
;     return bon;
; }
.LBB0_1115:
	v_add_u32_e32 v28, v120, v130
	s_waitcnt lgkmcnt(0)
	s_barrier
	ds_read_b128 v[108:111], v28
	v_lshl_add_u64 v[112:113], s[92:93], 0, v[100:101]
	v_add_co_u32_e32 v112, vcc, s68, v112
	s_cmpk_gt_u32 s14, 0xfd
	s_waitcnt lgkmcnt(0)
	v_add_f32_e32 v28, v108, v109
	v_add_f32_e32 v33, v110, v111
	v_add_f32_e32 v28, v28, v33
	v_bfe_u32 v33, v28, 16, 1
	v_add3_u32 v28, v28, v33, s67
	v_addc_co_u32_e32 v113, vcc, 0, v113, vcc
	global_store_short_d16_hi v[112:113], v28, off
	v_add_u32_e32 v28, v120, v131
	ds_read_b128 v[108:111], v28
	s_cselect_b64 s[52:53], -1, 0
	s_and_b64 vcc, exec, s[52:53]
	s_waitcnt lgkmcnt(0)
	v_add_f32_e32 v28, v108, v109
	v_add_f32_e32 v33, v110, v111
	v_add_f32_e32 v28, v28, v33
	v_bfe_u32 v33, v28, 16, 1
	v_add3_u32 v28, v28, v33, s67
	global_store_short_d16_hi v[112:113], v28, off offset:2048
	s_cbranch_vccnz .LBB0_1106
	v_lshlrev_b32_e32 v108, 16, v76
	v_and_b32_e32 v109, 0xffff0000, v76
	v_lshlrev_b32_e32 v110, 16, v62
	v_and_b32_e32 v111, 0xffff0000, v62
	v_pk_add_f32 v[110:111], v[110:111], v[108:109] neg_lo:[0,1] neg_hi:[0,1]
	v_lshlrev_b32_e32 v140, 16, v63
	v_pk_fma_f32 v[144:145], v[6:7], v[110:111], v[108:109]
	v_lshlrev_b32_e32 v110, 16, v77
	v_and_b32_e32 v111, 0xffff0000, v77
	v_and_b32_e32 v141, 0xffff0000, v63
	v_pk_add_f32 v[140:141], v[140:141], v[110:111] neg_lo:[0,1] neg_hi:[0,1]
	v_lshlrev_b32_e32 v118, 16, v64
	v_and_b32_e32 v119, 0xffff0000, v64
	v_pk_fma_f32 v[146:147], v[8:9], v[140:141], v[110:111]
	v_lshlrev_b32_e32 v140, 16, v54
	v_and_b32_e32 v141, 0xffff0000, v54
	s_waitcnt vmcnt(3)
	v_lshlrev_b32_e32 v142, 16, v86
	v_and_b32_e32 v143, 0xffff0000, v86
	v_pk_add_f32 v[140:141], v[140:141], v[118:119] neg_lo:[0,1] neg_hi:[0,1]
	v_pk_add_f32 v[148:149], v[142:143], -1.0 op_sel_hi:[1,0]
	v_pk_fma_f32 v[140:141], v[2:3], v[140:141], v[118:119]
	v_pk_fma_f32 v[148:149], v[18:19], v[148:149], 1.0 op_sel_hi:[1,1,0]
	v_pk_mul_f32 v[154:155], v[14:15], v[140:141]
	v_pk_mul_f32 v[148:149], v[140:141], v[148:149]
	v_cvt_f32_f16_sdwa v141, v72 dst_sel:DWORD dst_unused:UNUSED_PAD src0_sel:WORD_1
	v_cvt_f32_f16_e32 v140, v72
	v_lshlrev_b32_e32 v114, 16, v56
	v_and_b32_e32 v115, 0xffff0000, v56
	v_lshlrev_b32_e32 v156, 16, v68
	v_and_b32_e32 v157, 0xffff0000, v68
	v_pk_add_f32 v[152:153], v[140:141], 1.0 op_sel_hi:[1,0] neg_lo:[1,0] neg_hi:[1,0]
	v_pk_add_f32 v[140:141], v[156:157], v[114:115] neg_lo:[0,1] neg_hi:[0,1]
	v_lshlrev_b32_e32 v116, 16, v65
	v_pk_fma_f32 v[164:165], v[10:11], v[140:141], v[114:115]
	v_and_b32_e32 v117, 0xffff0000, v65
	v_pk_mul_f32 v[140:141], v[164:165], v[148:149]
	v_pk_mul_f32 v[150:151], v[154:155], v[154:155]
	v_fma_f32 v33, v22, v140, 0
	v_fmac_f32_e32 v33, v23, v141
	v_lshlrev_b32_e32 v140, 16, v55
	v_and_b32_e32 v141, 0xffff0000, v55
	v_pk_add_f32 v[140:141], v[140:141], v[116:117] neg_lo:[0,1] neg_hi:[0,1]
	v_add_f32_e32 v28, v150, v151
	v_pk_fma_f32 v[140:141], v[4:5], v[140:141], v[116:117]
	v_pk_mul_f32 v[142:143], v[154:155], v[142:143]
	v_pk_mul_f32 v[158:159], v[16:17], v[140:141]
	v_pk_mul_f32 v[160:161], v[158:159], v[158:159]
	v_add_f32_e32 v28, v160, v28
	v_add_f32_e32 v28, v161, v28
	v_lshlrev_b32_e32 v156, 16, v87
	s_nop 0
	v_add_f32_dpp v28, v28, v28 row_ror:1 row_mask:0xf bank_mask:0xf bound_ctrl:1
	v_and_b32_e32 v157, 0xffff0000, v87
	v_lshlrev_b32_e32 v112, 16, v57
	v_add_f32_dpp v28, v28, v28 row_ror:2 row_mask:0xf bank_mask:0xf bound_ctrl:1
	v_and_b32_e32 v113, 0xffff0000, v57
	v_pk_add_f32 v[162:163], v[156:157], -1.0 op_sel_hi:[1,0]
	v_add_f32_dpp v28, v28, v28 row_ror:4 row_mask:0xf bank_mask:0xf bound_ctrl:1
	v_pk_fma_f32 v[150:151], v[20:21], v[162:163], 1.0 op_sel_hi:[1,1,0]
	v_pk_mul_f32 v[164:165], v[164:165], 1.0 op_sel_hi:[1,0]
	v_add_f32_dpp v28, v28, v28 row_ror:8 row_mask:0xf bank_mask:0xf bound_ctrl:1
	v_max_f32_e32 v28, 0x179abe15, v28
	v_rsq_f32_e32 v28, v28
	v_pk_mul_f32 v[150:151], v[140:141], v[150:151]
	v_pk_mul_f32 v[140:141], v[158:159], v[156:157]
	v_pk_mul_f32 v[160:161], v[142:143], v[28:29] op_sel_hi:[1,0]
	v_lshlrev_b32_e32 v142, 16, v69
	v_and_b32_e32 v143, 0xffff0000, v69
	v_pk_add_f32 v[142:143], v[142:143], v[112:113] neg_lo:[0,1] neg_hi:[0,1]
	v_pk_mul_f32 v[162:163], v[140:141], v[28:29] op_sel_hi:[1,0]
	v_pk_fma_f32 v[166:167], v[12:13], v[142:143], v[112:113]
	v_pk_mul_f32 v[156:157], v[154:155], v[28:29] op_sel_hi:[1,0] neg_lo:[0,1] neg_hi:[0,1]
	v_pk_mul_f32 v[142:143], v[166:167], v[150:151]
	v_fmac_f32_e32 v33, v24, v142
	v_cvt_f32_f16_sdwa v155, v73 dst_sel:DWORD dst_unused:UNUSED_PAD src0_sel:WORD_1
	v_cvt_f32_f16_e32 v154, v73
	v_fmac_f32_e32 v33, v25, v143
	s_nop 1
	v_add_f32_dpp v33, v33, v33 row_ror:1 row_mask:0xf bank_mask:0xf bound_ctrl:1
	s_nop 1
	v_add_f32_dpp v33, v33, v33 row_ror:2 row_mask:0xf bank_mask:0xf bound_ctrl:1
	s_nop 1
	v_add_f32_dpp v33, v33, v33 row_ror:4 row_mask:0xf bank_mask:0xf bound_ctrl:1
	v_mov_b32_e32 v81, 0
	v_pk_add_f32 v[154:155], v[154:155], 1.0 op_sel_hi:[1,0] neg_lo:[1,0] neg_hi:[1,0]
	s_nop 0
	v_mov_b32_dpp v81, v33 row_ror:8 row_mask:0xf bank_mask:0xf
	v_pk_mul_f32 v[158:159], v[158:159], v[28:29] op_sel_hi:[1,0] neg_lo:[0,1] neg_hi:[0,1]
	v_pk_mul_f32 v[166:167], v[166:167], 1.0 op_sel_hi:[1,0]
	v_pk_mov_b32 v[174:175], v[152:153], v[152:153] op_sel:[0,1]
	v_pk_mov_b32 v[176:177], v[154:155], v[154:155] op_sel:[0,1]
	v_pk_mov_b32 v[178:179], v[148:149], v[148:149] op_sel:[0,1]
	v_pk_mov_b32 v[180:181], v[150:151], v[150:151] op_sel:[0,1]
	v_pk_mov_b32 v[182:183], v[156:157], v[156:157] op_sel:[0,1]
	v_pk_mov_b32 v[184:185], v[158:159], v[158:159] op_sel:[0,1]
	v_pk_mov_b32 v[186:187], v[160:161], v[160:161] op_sel:[0,1]
	v_pk_mov_b32 v[188:189], v[162:163], v[162:163] op_sel:[0,1]
	v_pk_mov_b32 v[190:191], v[164:165], v[164:165] op_sel:[0,1]
	v_pk_mov_b32 v[192:193], v[166:167], v[166:167] op_sel:[0,1]
	v_mov_b32_e32 v194, v127
	ds_write_b128 v127, v[144:147] offset:1280
	s_and_saveexec_b64 s[56:57], s[4:5]
	s_or_b64 exec, exec, s[56:57]
	s_waitcnt vmcnt(4)
; #define LAS __attribute__((address_space(3)))
; __device__ __forceinline__ float scan_prepare(const ScanRegs& R, const u32x2 qr_, const u32x2 qk_, const u32x2 qv_, LAS float* slot, int cq, const f32x4 mur, const f32x4 muk, const f32x4 muv, const f32x4 kkc, const f32x4 kac, const f32x4 rkc) {
;     float pr[4], pk[4], pv[4], qr[4], qk[4], qv[4], av[4], om[4];
;     unpack4(R.pr, pr); unpack4(R.pk, pk); unpack4(R.pv, pv); unpack4(qr_, qr); unpack4(qk_, qk); unpack4(qv_, qv); unpack4(R.as, av);
;     om[0] = f16_to_f((unsigned short)(R.wl.x & 0xffffu)); om[1] = f16_to_f((unsigned short)(R.wl.x >> 16)); om[2] = f16_to_f((unsigned short)(R.wl.y & 0xffffu)); om[3] = f16_to_f((unsigned short)(R.wl.y >> 16));
;     float rr[4], vv[4], kn[4], k2[4], dec[4], bu[4];
;     float ssq = 0.f, bon = 0.f, c1 = 0.f, c2 = 0.f;
; #pragma unroll
;     for (int j = 0; j < 4; ++j) {
;         rr[j] = pr[j] + (qr[j] - pr[j]) * mur[j]; const float kk0 = pk[j] + (qk[j] - pk[j]) * muk[j]; vv[j] = pv[j] + (qv[j] - pv[j]) * muv[j];
;         dec[j] = 1.0f - om[j];
;         kn[j] = kk0 * kkc[j]; ssq += kn[j] * kn[j];
;         k2[j] = kk0 * (1.0f + (av[j] - 1.0f) * kac[j]);
;         const float t = rr[j] * k2[j]; bon += t * rkc[j]; c2 += t;
;         bu[j] = kn[j] * av[j]; c1 += bu[j] * rr[j];
;     }
;     ssq += dpp_f<0x121>(ssq); bon += dpp_f<0x121>(bon); c1 += dpp_f<0x121>(c1); c2 += dpp_f<0x121>(c2);
;     ssq += dpp_f<0x122>(ssq); bon += dpp_f<0x122>(bon); c1 += dpp_f<0x122>(c1); c2 += dpp_f<0x122>(c2);
;     ssq += dpp_f<0x124>(ssq); bon += dpp_f<0x124>(bon); c1 += dpp_f<0x124>(c1); c2 += dpp_f<0x124>(c2);
;     ssq += dpp_f<0x128>(ssq); bon += dpp_f<0x128>(bon); c1 += dpp_f<0x128>(c1); c2 += dpp_f<0x128>(c2);
;     const float inv = __builtin_amdgcn_rsqf(fmaxf(ssq, 1e-24f));
;     f32x4 o_al, o_be, o_wr;
; #pragma unroll
;     for (int j = 0; j < 4; ++j) { o_al[j] = -(kn[j] * inv); o_be[j] = bu[j] * inv; o_wr[j] = dec[j] * rr[j]; }
;     LAS f32x4* s4 = (LAS f32x4*)slot;
;     s4[cq] = (f32x4){dec[0], dec[1], dec[2], dec[3]}; s4[16 + cq] = (f32x4){k2[0], k2[1], k2[2], k2[3]}; s4[32 + cq] = o_al; s4[48 + cq] = o_be; s4[64 + cq] = o_wr;
;     s4[80 + cq] = (f32x4){vv[0], vv[1], vv[2], vv[3]};
;     if (cq == 0) *(LAS f32x2*)(slot + 384) = (f32x2){c1 * inv, c2};
;     return bon;
; }
	v_lshlrev_b32_e32 v140, 16, v96
	v_and_b32_e32 v141, 0xffff0000, v96
	s_waitcnt vmcnt(2)
	v_lshlrev_b32_e32 v142, 16, v102
	v_and_b32_e32 v143, 0xffff0000, v102
	v_pk_add_f32 v[118:119], v[118:119], v[140:141] neg_lo:[0,1] neg_hi:[0,1]
	v_lshlrev_b32_e32 v150, 16, v103
	v_pk_fma_f32 v[118:119], v[2:3], v[118:119], v[140:141]
	v_pk_add_f32 v[140:141], v[142:143], -1.0 op_sel_hi:[1,0]
	v_pk_mul_f32 v[146:147], v[14:15], v[118:119]
	v_pk_fma_f32 v[140:141], v[18:19], v[140:141], 1.0 op_sel_hi:[1,1,0]
	v_pk_mul_f32 v[152:153], v[146:147], v[142:143]
	v_pk_mul_f32 v[140:141], v[140:141], v[118:119]
	v_cvt_f32_f16_sdwa v119, v98 dst_sel:DWORD dst_unused:UNUSED_PAD src0_sel:WORD_1
	v_cvt_f32_f16_e32 v118, v98
	v_lshlrev_b32_e32 v142, 16, v84
	v_and_b32_e32 v143, 0xffff0000, v84
	v_pk_add_f32 v[114:115], v[114:115], v[142:143] neg_lo:[0,1] neg_hi:[0,1]
	v_pk_add_f32 v[144:145], v[118:119], 1.0 op_sel_hi:[1,0] neg_lo:[1,0] neg_hi:[1,0]
	v_pk_fma_f32 v[118:119], v[10:11], v[114:115], v[142:143]
	v_pk_mul_f32 v[148:149], v[146:147], v[146:147]
	v_pk_mul_f32 v[114:115], v[118:119], v[140:141]
	v_fma_f32 v156, v22, v114, 0
	v_fmac_f32_e32 v156, v23, v115
	v_lshlrev_b32_e32 v114, 16, v97
	v_and_b32_e32 v115, 0xffff0000, v97
	v_pk_add_f32 v[116:117], v[116:117], v[114:115] neg_lo:[0,1] neg_hi:[0,1]
	v_add_f32_e32 v28, v148, v149
	v_pk_fma_f32 v[114:115], v[4:5], v[116:117], v[114:115]
	v_and_b32_e32 v151, 0xffff0000, v103
	v_pk_mul_f32 v[116:117], v[16:17], v[114:115]
	v_pk_add_f32 v[154:155], v[150:151], -1.0 op_sel_hi:[1,0]
	v_pk_mul_f32 v[142:143], v[116:117], v[116:117]
	v_lshlrev_b32_e32 v160, 16, v94
	v_add_f32_e32 v28, v142, v28
	v_add_f32_e32 v28, v143, v28
	v_pk_fma_f32 v[142:143], v[20:21], v[154:155], 1.0 op_sel_hi:[1,1,0]
	v_and_b32_e32 v161, 0xffff0000, v94
	v_add_f32_dpp v28, v28, v28 row_ror:1 row_mask:0xf bank_mask:0xf bound_ctrl:1
	v_pk_mul_f32 v[142:143], v[142:143], v[114:115]
	v_pk_mul_f32 v[114:115], v[116:117], v[150:151]
	v_add_f32_dpp v28, v28, v28 row_ror:2 row_mask:0xf bank_mask:0xf bound_ctrl:1
	v_lshlrev_b32_e32 v162, 16, v95
	v_and_b32_e32 v163, 0xffff0000, v95
	v_add_f32_dpp v28, v28, v28 row_ror:4 row_mask:0xf bank_mask:0xf bound_ctrl:1
	v_pk_add_f32 v[108:109], v[108:109], v[160:161] neg_lo:[0,1] neg_hi:[0,1]
	v_pk_add_f32 v[110:111], v[110:111], v[162:163] neg_lo:[0,1] neg_hi:[0,1]
	v_add_f32_dpp v28, v28, v28 row_ror:8 row_mask:0xf bank_mask:0xf bound_ctrl:1
	v_max_f32_e32 v28, 0x179abe15, v28
	v_rsq_f32_e32 v28, v28
	v_pk_fma_f32 v[110:111], v[8:9], v[110:111], v[162:163]
	v_pk_fma_f32 v[108:109], v[6:7], v[108:109], v[160:161]
	v_pk_mul_f32 v[150:151], v[116:117], v[28:29] op_sel_hi:[1,0] neg_lo:[0,1] neg_hi:[0,1]
	v_lshlrev_b32_e32 v116, 16, v85
	v_and_b32_e32 v117, 0xffff0000, v85
	v_pk_add_f32 v[112:113], v[112:113], v[116:117] neg_lo:[0,1] neg_hi:[0,1]
	v_pk_mul_f32 v[154:155], v[114:115], v[28:29] op_sel_hi:[1,0]
	v_pk_fma_f32 v[158:159], v[12:13], v[112:113], v[116:117]
	v_pk_mul_f32 v[148:149], v[146:147], v[28:29] op_sel_hi:[1,0] neg_lo:[0,1] neg_hi:[0,1]
	v_pk_mul_f32 v[112:113], v[158:159], v[142:143]
	v_fmac_f32_e32 v156, v24, v112
	v_cvt_f32_f16_sdwa v147, v99 dst_sel:DWORD dst_unused:UNUSED_PAD src0_sel:WORD_1
	v_cvt_f32_f16_e32 v146, v99
	v_fmac_f32_e32 v156, v25, v113
	s_nop 1
	v_add_f32_dpp v114, v156, v156 row_ror:1 row_mask:0xf bank_mask:0xf bound_ctrl:1
	s_nop 1
	v_add_f32_dpp v114, v114, v114 row_ror:2 row_mask:0xf bank_mask:0xf bound_ctrl:1
	s_nop 1
	v_add_f32_dpp v112, v114, v114 row_ror:4 row_mask:0xf bank_mask:0xf bound_ctrl:1
	v_mov_b32_e32 v113, 0
	v_pk_add_f32 v[146:147], v[146:147], 1.0 op_sel_hi:[1,0] neg_lo:[1,0] neg_hi:[1,0]
	s_nop 0
	v_mov_b32_dpp v113, v112 row_ror:8 row_mask:0xf bank_mask:0xf
	v_pk_mul_f32 v[152:153], v[152:153], v[28:29] op_sel_hi:[1,0]
	v_pk_mul_f32 v[156:157], v[118:119], 1.0 op_sel_hi:[1,0]
	v_pk_mul_f32 v[158:159], v[158:159], 1.0 op_sel_hi:[1,0]
	ds_write_b128 v129, v[108:111] offset:1280
	v_pk_mul_f32 v[196:197], v[174:175], v[144:145]
	v_pk_mul_f32 v[198:199], v[176:177], v[146:147]
	ds_bpermute_b32 v200, v233, v196
	ds_bpermute_b32 v201, v233, v197
	ds_bpermute_b32 v202, v233, v198
	ds_bpermute_b32 v203, v233, v199
	s_waitcnt lgkmcnt(0)
	v_fma_f32 v200, v200, v235, v236
	v_fma_f32 v201, v201, v235, v236
	v_fma_f32 v202, v202, v235, v236
	v_fma_f32 v203, v203, v235, v236
	v_pk_mul_f32 v[204:205], v[196:197], v[200:201]
	v_pk_mul_f32 v[206:207], v[198:199], v[202:203]
	v_mov_b32_e32 v208, v204
	v_mov_b32_e32 v209, v205
	v_mov_b32_e32 v210, v206
	v_mov_b32_e32 v211, v207
	v_permlane32_swap_b32 v204, v208
	v_permlane32_swap_b32 v205, v209
	v_permlane32_swap_b32 v206, v210
	v_permlane32_swap_b32 v207, v211
	v_fma_f32 v208, v204, v237, v238
	v_fma_f32 v209, v205, v237, v238
	v_fma_f32 v210, v206, v237, v238
	v_fma_f32 v211, v207, v237, v238
	v_pk_mul_f32 v[212:213], v[200:201], v[208:209]
	v_pk_mul_f32 v[214:215], v[202:203], v[210:211]
	v_pk_mul_f32 v[216:217], v[212:213], v[174:175]
	v_pk_mul_f32 v[218:219], v[214:215], v[176:177]
	v_pk_mul_f32 v[220:221], v[216:217], v[144:145]
	v_pk_mul_f32 v[222:223], v[218:219], v[146:147]
	v_rcp_f32_e32 v224, v216
	v_rcp_f32_e32 v225, v217
	v_rcp_f32_e32 v226, v218
	v_rcp_f32_e32 v227, v219
	v_rcp_f32_e32 v228, v220
	v_rcp_f32_e32 v229, v221
	v_rcp_f32_e32 v230, v222
	v_rcp_f32_e32 v231, v223
	s_nop 0
	v_pk_mul_f32 v[182:183], v[182:183], v[212:213]
	v_pk_mul_f32 v[184:185], v[184:185], v[214:215]
	v_pk_mul_f32 v[178:179], v[178:179], v[224:225]
	v_pk_mul_f32 v[180:181], v[180:181], v[226:227]
	ds_write_b128 v194, v[178:181] offset:256
	v_pk_mul_f32 v[186:187], v[186:187], v[224:225]
	v_pk_mul_f32 v[188:189], v[188:189], v[226:227]
	ds_write_b128 v194, v[182:185] offset:512
	v_pk_mul_f32 v[190:191], v[190:191], v[216:217]
	v_pk_mul_f32 v[192:193], v[192:193], v[218:219]
	ds_write_b128 v194, v[186:189] offset:768
	v_pk_mul_f32 v[240:241], v[140:141], v[228:229]
	v_pk_mul_f32 v[242:243], v[142:143], v[230:231]
	ds_write_b128 v194, v[190:193] offset:1024
	v_pk_mul_f32 v[244:245], v[148:149], v[216:217]
	v_pk_mul_f32 v[246:247], v[150:151], v[218:219]
	ds_write_b128 v129, v[220:223]
	v_pk_mul_f32 v[196:197], v[152:153], v[228:229]
	v_pk_mul_f32 v[198:199], v[154:155], v[230:231]
	ds_write_b128 v129, v[240:243] offset:256
	v_pk_mul_f32 v[200:201], v[156:157], v[220:221]
	v_pk_mul_f32 v[202:203], v[158:159], v[222:223]
	ds_write_b128 v129, v[244:247] offset:512
	ds_write_b128 v129, v[196:199] offset:768
	ds_write_b128 v129, v[200:203] offset:1024
	s_sleep 12
	s_and_saveexec_b64 s[56:57], s[4:5]
	s_cbranch_execz .LBB0_1123
	s_or_b64 exec, exec, s[56:57]
	s_and_saveexec_b64 s[56:57], s[44:45]
	s_cbranch_execnz .LBB0_1124
